# v097 + MLA fast path control trims: early rescale compare, no s42 flag, loop test ahead of last two MFMAs, key-index register updated once at exit
# speedup vs baseline: 1.0122x; 1.0025x over previous
.Lmla_fast:
	s_mov_b32 s42, s30
	s_and_b32 s8, s30, 3
	s_mulk_i32 s8, 0x6400
	s_add_i32 s8, s8, 0
	v_add3_u32 v142, s8, v144, v145
	v_add3_u32 v0, s8, v143, v132
	ds_read_b128 v[194:197], v0
	ds_read_b128 v[150:153], v0 offset:32
	ds_read_b128 v[158:161], v0 offset:64
	ds_read_b128 v[162:165], v0 offset:96
	ds_read_b128 v[174:177], v0 offset:128
	ds_read_b128 v[178:181], v0 offset:160
	s_bitcmp1_b32 s30, 0
	s_cbranch_scc1 .Lmla_fast_havek_o

.Lmla_fast_nodma_e:
	s_waitcnt lgkmcnt(0)
	v_mfma_f32_32x32x16_bf16 v[50:65], v[194:197], v[74:77], v[234:249]
	ds_read_b128 v[194:197], v0 offset:6656
	v_add_f32_e32 v254, v202, v203
	v_add_f32_e32 v255, v204, v205
	v_add_f32_e32 v254, v254, v206
	v_add_f32_e32 v255, v255, v207
	v_add_f32_e32 v254, v254, v208
	v_add_f32_e32 v255, v255, v209
	v_mfma_f32_32x32x16_bf16 v[50:65], v[150:153], v[78:81], v[50:65]
	ds_read_b128 v[150:153], v0 offset:6688
	v_add_f32_e32 v254, v254, v210
	v_add_f32_e32 v255, v255, v211
	v_add_f32_e32 v254, v254, v212
	v_add_f32_e32 v255, v255, v213
	v_add_f32_e32 v254, v254, v214
	v_add_f32_e32 v255, v255, v215
	v_mfma_f32_32x32x16_bf16 v[50:65], v[158:161], v[82:85], v[50:65]
	ds_read_b128 v[158:161], v0 offset:6720
	v_add_f32_e32 v254, v254, v216
	v_add_f32_e32 v255, v255, v217
	v_add_f32_e32 v254, v254, v218
	v_add_f32_e32 v255, v255, v219
	v_add_f32_e32 v254, v254, v220
	v_mfma_f32_32x32x16_bf16 v[50:65], v[162:165], v[86:89], v[50:65]
	ds_read_b128 v[162:165], v0 offset:6752
	v_add_f32_e32 v255, v255, v221
	v_add_f32_e32 v254, v254, v222
	v_add_f32_e32 v255, v255, v223
	v_add_f32_e32 v254, v254, v224
	v_add_f32_e32 v255, v255, v225
	v_mfma_f32_32x32x16_bf16 v[50:65], v[174:177], v[90:93], v[50:65]
	ds_read_b128 v[174:177], v0 offset:6784
	v_add_f32_e32 v254, v254, v226
	v_add_f32_e32 v255, v255, v227
	v_add_f32_e32 v254, v254, v228
	v_add_f32_e32 v255, v255, v229
	v_add_f32_e32 v254, v254, v230
	v_mfma_f32_32x32x16_bf16 v[50:65], v[178:181], v[94:97], v[50:65]
	ds_read_b128 v[178:181], v0 offset:6816
	v_add_f32_e32 v255, v255, v231
	v_add_f32_e32 v254, v254, v232
	v_add_f32_e32 v255, v255, v233
	v_add_f32_e32 v254, v254, v255
	v_add_f32_e32 v147, v147, v254
	v_cmp_lt_f32_e32 vcc, 0x44800000, v254
	s_waitcnt lgkmcnt(5)
	v_mfma_f32_32x32x16_bf16 v[34:49], v[194:197], v[74:77], v[234:249]
	ds_read_b64_tr_b16 v[126:127], v142 offset:13312
	ds_read_b64_tr_b16 v[128:129], v142 offset:14848
	ds_read_b64_tr_b16 v[124:125], v142 offset:14912
	ds_read_b64_tr_b16 v[122:123], v142 offset:13376
	s_waitcnt lgkmcnt(8)
	v_mfma_f32_32x32x16_bf16 v[34:49], v[150:153], v[78:81], v[34:49]
	ds_read_b64_tr_b16 v[118:119], v142 offset:16384
	ds_read_b64_tr_b16 v[120:121], v142 offset:17920
	ds_read_b64_tr_b16 v[116:117], v142 offset:17984
	ds_read_b64_tr_b16 v[114:115], v142 offset:16448
	v_exp_f32_e32 v202, v50
	v_exp_f32_e32 v203, v51
	v_exp_f32_e32 v204, v52
	s_waitcnt lgkmcnt(11)
	v_mfma_f32_32x32x16_bf16 v[34:49], v[158:161], v[82:85], v[34:49]
	ds_read_b64_tr_b16 v[110:111], v142 offset:19456
	ds_read_b64_tr_b16 v[112:113], v142 offset:20992
	ds_read_b64_tr_b16 v[108:109], v142 offset:21056
	ds_read_b64_tr_b16 v[106:107], v142 offset:19520
	v_exp_f32_e32 v205, v53
	v_exp_f32_e32 v206, v54
	v_exp_f32_e32 v207, v55
	s_waitcnt lgkmcnt(11)
	v_mfma_f32_32x32x16_bf16 v[34:49], v[162:165], v[86:89], v[34:49]
	ds_read_b64_tr_b16 v[102:103], v142 offset:22528
	ds_read_b64_tr_b16 v[104:105], v142 offset:24064
	ds_read_b64_tr_b16 v[100:101], v142 offset:24128
	ds_read_b64_tr_b16 v[98:99], v142 offset:22592
	v_exp_f32_e32 v208, v56
	v_exp_f32_e32 v209, v57
	v_exp_f32_e32 v210, v58
	v_mfma_f32_32x32x16_bf16 v[34:49], v[174:177], v[90:93], v[34:49]
	v_exp_f32_e32 v211, v59
	v_exp_f32_e32 v212, v60
	v_exp_f32_e32 v213, v61
	v_exp_f32_e32 v214, v62
	v_mfma_f32_32x32x16_bf16 v[34:49], v[178:181], v[94:97], v[34:49]
.Lmla_fast_nostag_e:
	v_exp_f32_e32 v215, v63
	v_exp_f32_e32 v216, v64
	v_exp_f32_e32 v217, v65
	s_cbranch_vccnz .Lmla_fast_rescale_e
.Lmla_fast_ok_e:
	v_cvt_pk_bf16_f32 v166, v202, v203
	v_cvt_pk_bf16_f32 v167, v204, v205
	v_cvt_pk_bf16_f32 v168, v206, v207
	v_cvt_pk_bf16_f32 v169, v208, v209
	s_waitcnt lgkmcnt(0)
	s_nop 0
	v_mfma_f32_32x32x16_bf16 v[18:33], v[126:129], v[166:169], v[18:33]
	s_add_i32 s8, s30, 1
	s_and_b32 s8, s8, 3
	s_mulk_i32 s8, 0x6400
	v_add3_u32 v0, s8, v143, v132
	v_add3_u32 v142, s8, v144, v145
	v_mfma_f32_32x32x16_bf16 v[2:17], v[122:125], v[166:169], v[2:17]
	v_cvt_pk_bf16_f32 v170, v210, v211
	v_cvt_pk_bf16_f32 v171, v212, v213
	v_cvt_pk_bf16_f32 v172, v214, v215
	v_cvt_pk_bf16_f32 v173, v216, v217
	v_exp_f32_e32 v218, v34
	v_exp_f32_e32 v219, v35
	v_mfma_f32_32x32x16_bf16 v[18:33], v[118:121], v[170:173], v[18:33]
	v_exp_f32_e32 v220, v36
	v_exp_f32_e32 v221, v37
	ds_read_b128 v[194:197], v0
	ds_read_b128 v[150:153], v0 offset:32
	v_mfma_f32_32x32x16_bf16 v[2:17], v[114:117], v[170:173], v[2:17]
	v_exp_f32_e32 v222, v38
	v_exp_f32_e32 v223, v39
	v_exp_f32_e32 v224, v40
	v_exp_f32_e32 v225, v41
	v_cvt_pk_bf16_f32 v166, v218, v219
	v_cvt_pk_bf16_f32 v167, v220, v221
	v_cvt_pk_bf16_f32 v168, v222, v223
	v_cvt_pk_bf16_f32 v169, v224, v225
	ds_read_b128 v[158:161], v0 offset:64
	ds_read_b128 v[162:165], v0 offset:96
	v_mfma_f32_32x32x16_bf16 v[18:33], v[110:113], v[166:169], v[18:33]
	v_exp_f32_e32 v226, v42
	v_exp_f32_e32 v227, v43
	v_exp_f32_e32 v228, v44
	v_mfma_f32_32x32x16_bf16 v[2:17], v[106:109], v[166:169], v[2:17]
	v_exp_f32_e32 v229, v45
	v_exp_f32_e32 v230, v46
	v_exp_f32_e32 v231, v47
	v_exp_f32_e32 v232, v48
	v_exp_f32_e32 v233, v49
	ds_read_b128 v[174:177], v0 offset:128
	ds_read_b128 v[178:181], v0 offset:160
	v_cvt_pk_bf16_f32 v170, v226, v227
	v_cvt_pk_bf16_f32 v171, v228, v229
	v_cvt_pk_bf16_f32 v172, v230, v231
	v_cvt_pk_bf16_f32 v173, v232, v233
	s_add_i32 s30, s30, 1
	s_add_i32 s31, s31, 64
	s_cmp_le_u32 s31, s4
	v_mfma_f32_32x32x16_bf16 v[18:33], v[102:105], v[170:173], v[18:33]
	v_mfma_f32_32x32x16_bf16 v[2:17], v[98:101], v[170:173], v[2:17]
	s_cbranch_scc0 .Lmla_fast_generic
.Lmla_fast_havek_o:
.Lmla_fast_nodma_o:
	s_waitcnt lgkmcnt(0)
	v_mfma_f32_32x32x16_bf16 v[50:65], v[194:197], v[74:77], v[234:249]
	ds_read_b128 v[194:197], v0 offset:6656
	v_add_f32_e32 v254, v202, v203
	v_add_f32_e32 v255, v204, v205
	v_add_f32_e32 v254, v254, v206
	v_add_f32_e32 v255, v255, v207
	v_add_f32_e32 v254, v254, v208
	v_add_f32_e32 v255, v255, v209
	v_mfma_f32_32x32x16_bf16 v[50:65], v[150:153], v[78:81], v[50:65]
	ds_read_b128 v[150:153], v0 offset:6688
	v_add_f32_e32 v254, v254, v210
	v_add_f32_e32 v255, v255, v211
	v_add_f32_e32 v254, v254, v212
	v_add_f32_e32 v255, v255, v213
	v_add_f32_e32 v254, v254, v214
	v_add_f32_e32 v255, v255, v215
	v_mfma_f32_32x32x16_bf16 v[50:65], v[158:161], v[82:85], v[50:65]
	ds_read_b128 v[158:161], v0 offset:6720
	v_add_f32_e32 v254, v254, v216
	v_add_f32_e32 v255, v255, v217
	v_add_f32_e32 v254, v254, v218
	v_add_f32_e32 v255, v255, v219
	v_add_f32_e32 v254, v254, v220
	v_mfma_f32_32x32x16_bf16 v[50:65], v[162:165], v[86:89], v[50:65]
	ds_read_b128 v[162:165], v0 offset:6752
	v_add_f32_e32 v255, v255, v221
	v_add_f32_e32 v254, v254, v222
	v_add_f32_e32 v255, v255, v223
	v_add_f32_e32 v254, v254, v224
	v_add_f32_e32 v255, v255, v225
	v_mfma_f32_32x32x16_bf16 v[50:65], v[174:177], v[90:93], v[50:65]
	ds_read_b128 v[174:177], v0 offset:6784
	v_add_f32_e32 v254, v254, v226
	v_add_f32_e32 v255, v255, v227
	v_add_f32_e32 v254, v254, v228
	v_add_f32_e32 v255, v255, v229
	v_add_f32_e32 v254, v254, v230
	v_mfma_f32_32x32x16_bf16 v[50:65], v[178:181], v[94:97], v[50:65]
	ds_read_b128 v[178:181], v0 offset:6816
	v_add_f32_e32 v255, v255, v231
	v_add_f32_e32 v254, v254, v232
	v_add_f32_e32 v255, v255, v233
	v_add_f32_e32 v254, v254, v255
	v_add_f32_e32 v147, v147, v254
	v_cmp_lt_f32_e32 vcc, 0x44800000, v254
	s_waitcnt lgkmcnt(5)
	v_mfma_f32_32x32x16_bf16 v[34:49], v[194:197], v[74:77], v[234:249]
	ds_read_b64_tr_b16 v[126:127], v142 offset:13312
	ds_read_b64_tr_b16 v[128:129], v142 offset:14848
	ds_read_b64_tr_b16 v[124:125], v142 offset:14912
	ds_read_b64_tr_b16 v[122:123], v142 offset:13376
	s_waitcnt lgkmcnt(8)
	v_mfma_f32_32x32x16_bf16 v[34:49], v[150:153], v[78:81], v[34:49]
	ds_read_b64_tr_b16 v[118:119], v142 offset:16384
	ds_read_b64_tr_b16 v[120:121], v142 offset:17920
	ds_read_b64_tr_b16 v[116:117], v142 offset:17984
	ds_read_b64_tr_b16 v[114:115], v142 offset:16448
	v_exp_f32_e32 v202, v50
	v_exp_f32_e32 v203, v51
	v_exp_f32_e32 v204, v52
	s_waitcnt lgkmcnt(11)
	v_mfma_f32_32x32x16_bf16 v[34:49], v[158:161], v[82:85], v[34:49]
	ds_read_b64_tr_b16 v[110:111], v142 offset:19456
	ds_read_b64_tr_b16 v[112:113], v142 offset:20992
	ds_read_b64_tr_b16 v[108:109], v142 offset:21056
	ds_read_b64_tr_b16 v[106:107], v142 offset:19520
	v_exp_f32_e32 v205, v53
	v_exp_f32_e32 v206, v54
	v_exp_f32_e32 v207, v55
	s_waitcnt lgkmcnt(11)
	v_mfma_f32_32x32x16_bf16 v[34:49], v[162:165], v[86:89], v[34:49]
	ds_read_b64_tr_b16 v[102:103], v142 offset:22528
	ds_read_b64_tr_b16 v[104:105], v142 offset:24064
	ds_read_b64_tr_b16 v[100:101], v142 offset:24128
	ds_read_b64_tr_b16 v[98:99], v142 offset:22592
	v_exp_f32_e32 v208, v56
	v_exp_f32_e32 v209, v57
	v_exp_f32_e32 v210, v58
	v_mfma_f32_32x32x16_bf16 v[34:49], v[174:177], v[90:93], v[34:49]
	v_exp_f32_e32 v211, v59
	v_exp_f32_e32 v212, v60
	v_exp_f32_e32 v213, v61
	v_exp_f32_e32 v214, v62
	v_mfma_f32_32x32x16_bf16 v[34:49], v[178:181], v[94:97], v[34:49]
	s_waitcnt vmcnt(0) lgkmcnt(0)
	s_barrier

.Lmla_fast_ok_o:
	v_cvt_pk_bf16_f32 v166, v202, v203
	v_cvt_pk_bf16_f32 v167, v204, v205
	v_cvt_pk_bf16_f32 v168, v206, v207
	v_cvt_pk_bf16_f32 v169, v208, v209
	s_waitcnt lgkmcnt(0)
	s_nop 0
	v_mfma_f32_32x32x16_bf16 v[18:33], v[126:129], v[166:169], v[18:33]
	s_add_i32 s8, s30, 1
	s_and_b32 s8, s8, 3
	s_mulk_i32 s8, 0x6400
	v_add3_u32 v0, s8, v143, v132
	v_add3_u32 v142, s8, v144, v145
	v_mfma_f32_32x32x16_bf16 v[2:17], v[122:125], v[166:169], v[2:17]
	v_cvt_pk_bf16_f32 v170, v210, v211
	v_cvt_pk_bf16_f32 v171, v212, v213
	v_cvt_pk_bf16_f32 v172, v214, v215
	v_cvt_pk_bf16_f32 v173, v216, v217
	v_exp_f32_e32 v218, v34
	v_exp_f32_e32 v219, v35
	v_mfma_f32_32x32x16_bf16 v[18:33], v[118:121], v[170:173], v[18:33]
	v_exp_f32_e32 v220, v36
	v_exp_f32_e32 v221, v37
	ds_read_b128 v[194:197], v0
	ds_read_b128 v[150:153], v0 offset:32
	v_mfma_f32_32x32x16_bf16 v[2:17], v[114:117], v[170:173], v[2:17]
	v_exp_f32_e32 v222, v38
	v_exp_f32_e32 v223, v39
	v_exp_f32_e32 v224, v40
	v_exp_f32_e32 v225, v41
	v_cvt_pk_bf16_f32 v166, v218, v219
	v_cvt_pk_bf16_f32 v167, v220, v221
	v_cvt_pk_bf16_f32 v168, v222, v223
	v_cvt_pk_bf16_f32 v169, v224, v225
	ds_read_b128 v[158:161], v0 offset:64
	ds_read_b128 v[162:165], v0 offset:96
	v_mfma_f32_32x32x16_bf16 v[18:33], v[110:113], v[166:169], v[18:33]
	v_exp_f32_e32 v226, v42
	v_exp_f32_e32 v227, v43
	v_exp_f32_e32 v228, v44
	v_mfma_f32_32x32x16_bf16 v[2:17], v[106:109], v[166:169], v[2:17]
	v_exp_f32_e32 v229, v45
	v_exp_f32_e32 v230, v46
	v_exp_f32_e32 v231, v47
	v_exp_f32_e32 v232, v48
	v_exp_f32_e32 v233, v49
	ds_read_b128 v[174:177], v0 offset:128
	ds_read_b128 v[178:181], v0 offset:160
	v_cvt_pk_bf16_f32 v170, v226, v227
	v_cvt_pk_bf16_f32 v171, v228, v229
	v_cvt_pk_bf16_f32 v172, v230, v231
	v_cvt_pk_bf16_f32 v173, v232, v233
	s_add_i32 s30, s30, 1
	s_add_i32 s31, s31, 64
	s_cmp_le_u32 s31, s4
	v_mfma_f32_32x32x16_bf16 v[18:33], v[102:105], v[170:173], v[18:33]
	v_mfma_f32_32x32x16_bf16 v[2:17], v[98:101], v[170:173], v[2:17]
	s_cbranch_scc1 .Lmla_fast_havek_e
	s_branch .Lmla_fast_generic
.Lmla_fast_generic:
	s_sub_i32 s42, s30, s42
	s_lshl_b32 s42, s42, 6
	v_subrev_u32_e32 v146, s42, v146
	s_cmp_lg_u32 s20, s30
	s_cbranch_scc1 .LBB0_478
	s_branch .LBB0_430
